# GLA output-unit row reductions (xor 1/2/4/8 steps) on DPP as well
# speedup vs baseline: 1.0135x; 1.0094x over previous
; #define LAS __attribute__((address_space(3)))
; __device__ __forceinline__ int crow16(int r, int hi) { return (r & 3) + 8 * (r >> 2) + 4 * hi; }
; __device__ __forceinline__ void gla_p3(CArgs& a, int l, int cc, int h, LAS float* L) {
;     ...
;     { const int ib = wid >> 2, eb = wid & 3; f32x16 acc = {};
; #pragma unroll
;       for (int ks = 0; ks < 4; ++ks) {
;           acc = __builtin_amdgcn_mfma_f32_32x32x16_bf16(ldfrag(B + GB_ATT, 32 * ib + r32, ks, hi), ldfrag(B + GB_VT, 32 * eb + r32, ks, hi), acc, 0, 0, 0);
;           acc = __builtin_amdgcn_mfma_f32_32x32x16_bf16(ldfrag(B + GB_QDF, 32 * ib + r32, ks, hi), ldfrag(B + GB_SFT, 32 * eb + r32, ks, hi), acc, 0, 0, 0);
;           acc = __builtin_amdgcn_mfma_f32_32x32x16_bf16(ldfrag(B + GB_QDB, 32 * ib + r32, ks, hi), ldfrag(B + GB_SBT, 32 * eb + r32, ks, hi), acc, 0, 0, 0); }
; #pragma unroll
;       for (int r = 0; r < 16; ++r) L[(32 * ib + crow16(r, hi)) * 128 + 32 * eb + r32] = acc[r]; }
;     __syncthreads();
;     const int i0 = (tid >> 5) * 4, e4 = (tid & 31) * 4;
;     bf16_t* Z = (bf16_t*)(a.ws + WS_HZ);
;     const f32x4 gn = *(const f32x4*)(a.in[I_CON] + l * 128 + e4);
; #pragma unroll
;     for (int r = 0; r < 4; ++r) { const f32x4 o = *(const LAS f32x4*)(L + (i0 + r) * 128 + e4);
;         float ss = (o.x * o.x + o.y * o.y) + (o.z * o.z + o.w * o.w);
; #pragma unroll
;         for (int m = 1; m < 32; m <<= 1) ss += __shfl_xor(ss, m);
;         const float rs = rsqrtf(ss * (1.f / 128.f) + EPS);
;         const size_t row = (size_t)cc * 64 + i0 + r;
;         const u32x2 gw = *(const u32x2*)(P + (size_t)(i0 + r) * INP + C_CG + h * 128 + e4);
;         const f32x4 y = o * rs * gn;
.LBB0_96:
	s_or_b64 exec, exec, s[42:43]
	v_ashrrev_i32_e32 v38, 8, v34
	v_lshl_or_b32 v2, v38, 5, v36
	s_movk_i32 s5, 0x90
	v_mul_lo_u32 v10, v2, s5
	s_add_i32 s5, 0, 0x15a00
	v_add3_u32 v30, s5, v10, v37
	s_waitcnt lgkmcnt(0)
	s_barrier
	v_bfe_u32 v39, v34, 6, 2
	ds_read_b128 v[2:5], v30
	v_lshl_or_b32 v6, v39, 5, v36
	v_mul_u32_u24_e32 v31, 0x90, v6
	v_add3_u32 v40, s17, v31, v37
	ds_read_b128 v[6:9], v40
	v_add3_u32 v41, 0, v10, v37
	ds_read_b128 v[18:21], v41 offset:33280
	s_waitcnt lgkmcnt(1)
	v_mfma_f32_32x32x16_bf16 v[2:17], v[2:5], v[6:9], 0
	s_add_i32 s5, 0, 0x17e00
	v_add3_u32 v42, s5, v31, v37
	ds_read_b128 v[22:25], v42
	ds_read_b128 v[26:29], v41 offset:42496
	s_add_i32 s5, 0, 0x1c600
	v_add3_u32 v37, s5, v31, v37
	v_and_b32_e32 v0, 0x7c, v0
	s_lshl_b32 s18, s4, 1
	s_waitcnt lgkmcnt(1)
	v_mfma_f32_32x32x16_bf16 v[2:17], v[18:21], v[22:25], v[2:17]
	ds_read_b128 v[18:21], v37
	s_ashr_i32 s23, s22, 31
	s_lshl_b64 s[4:5], s[22:23], 18
	s_add_u32 s4, s56, s4
	s_addc_u32 s5, s57, s5
	s_waitcnt lgkmcnt(0)
	v_mfma_f32_32x32x16_bf16 v[2:17], v[26:29], v[18:21], v[2:17]
	ds_read_b128 v[18:21], v30 offset:32
	ds_read_b128 v[22:25], v40 offset:32
	s_waitcnt lgkmcnt(0)
	v_mfma_f32_32x32x16_bf16 v[2:17], v[18:21], v[22:25], v[2:17]
	ds_read_b128 v[18:21], v41 offset:33312
	ds_read_b128 v[22:25], v42 offset:32
	s_waitcnt lgkmcnt(0)
	v_mfma_f32_32x32x16_bf16 v[2:17], v[18:21], v[22:25], v[2:17]
	ds_read_b128 v[18:21], v41 offset:42528
	ds_read_b128 v[22:25], v37 offset:32
	s_waitcnt lgkmcnt(0)
	v_mfma_f32_32x32x16_bf16 v[2:17], v[18:21], v[22:25], v[2:17]
	ds_read_b128 v[18:21], v30 offset:64
	ds_read_b128 v[22:25], v40 offset:64
	s_waitcnt lgkmcnt(0)
	v_mfma_f32_32x32x16_bf16 v[2:17], v[18:21], v[22:25], v[2:17]
	ds_read_b128 v[18:21], v41 offset:33344
	ds_read_b128 v[22:25], v42 offset:64
	s_waitcnt lgkmcnt(0)
	v_mfma_f32_32x32x16_bf16 v[2:17], v[18:21], v[22:25], v[2:17]
	ds_read_b128 v[22:25], v41 offset:42560
	ds_read_b128 v[26:29], v37 offset:64
	ds_read_b128 v[30:33], v30 offset:96
	v_lshlrev_b32_e32 v19, 11, v35
	v_ashrrev_i32_e32 v20, 3, v34
	v_lshlrev_b32_e32 v34, 14, v38
	v_lshlrev_b32_e32 v21, 2, v36
	v_lshlrev_b32_e32 v35, 7, v39
	s_waitcnt lgkmcnt(1)
	v_mfma_f32_32x32x16_bf16 v[2:17], v[22:25], v[26:29], v[2:17]
	ds_read_b128 v[22:25], v40 offset:96
	ds_read_b128 v[26:29], v41 offset:33376
	v_and_b32_e32 v18, -4, v20
	v_lshlrev_b32_e32 v36, 2, v0
	v_lshlrev_b32_e32 v0, 1, v0
	s_waitcnt lgkmcnt(1)
	v_mfma_f32_32x32x16_bf16 v[2:17], v[30:33], v[22:25], v[2:17]
	ds_read_b128 v[22:25], v42 offset:96
	v_add3_u32 v30, 0, v34, v19
	v_add3_u32 v21, v30, v35, v21
	ds_read_b128 v[30:33], v41 offset:42592
	v_ashrrev_i32_e32 v19, 31, v18
	s_waitcnt lgkmcnt(1)
	v_mfma_f32_32x32x16_bf16 v[2:17], v[26:29], v[22:25], v[2:17]
	ds_read_b128 v[22:25], v37 offset:96
	v_lshlrev_b64 v[26:27], 13, v[18:19]
	v_lshl_add_u64 v[26:27], s[20:21], 0, v[26:27]
	v_lshl_add_u64 v[26:27], v[26:27], 0, s[18:19]
	v_lshl_add_u64 v[26:27], v[26:27], 0, v[0:1]
	v_add_co_u32_e32 v26, vcc, s10, v26
	s_waitcnt lgkmcnt(0)
	v_mfma_f32_32x32x16_bf16 v[2:17], v[30:33], v[22:25], v[2:17]
	v_addc_co_u32_e32 v27, vcc, 0, v27, vcc
	s_nop 10
	ds_write2st64_b32 v21, v2, v3 offset1:2
	ds_write2st64_b32 v21, v4, v5 offset0:4 offset1:6
	ds_write2st64_b32 v21, v6, v7 offset0:16 offset1:18
	ds_write2st64_b32 v21, v8, v9 offset0:20 offset1:22
	ds_write2st64_b32 v21, v10, v11 offset0:32 offset1:34
	ds_write2st64_b32 v21, v12, v13 offset0:36 offset1:38
	ds_write2st64_b32 v21, v14, v15 offset0:48 offset1:50
	ds_write2st64_b32 v21, v16, v17 offset0:52 offset1:54
	s_waitcnt lgkmcnt(0)
	s_barrier
	global_load_dwordx2 v[10:11], v[26:27], off offset:2688
	global_load_dwordx4 v[2:5], v36, s[52:53]
	v_add_co_u32_e32 v76, vcc, 0x2000, v26
	s_nop 1
	v_addc_co_u32_e32 v77, vcc, 0, v27, vcc
	global_load_dwordx2 v[80:81], v[76:77], off offset:2688
	v_add_co_u32_e32 v76, vcc, 0x2000, v76
	s_nop 1
	v_addc_co_u32_e32 v77, vcc, 0, v77, vcc
	global_load_dwordx2 v[82:83], v[76:77], off offset:2688
	v_add_co_u32_e32 v76, vcc, 0x2000, v76
	s_nop 1
	v_addc_co_u32_e32 v77, vcc, 0, v77, vcc
	global_load_dwordx2 v[84:85], v[76:77], off offset:2688
	v_add_u32_e32 v22, 0, v36
	v_lshl_add_u32 v6, v18, 9, v22
	ds_read_b128 v[6:9], v6
	v_and_b32_e32 v12, 64, v223
	v_xor_b32_e32 v13, 1, v223
	v_add_u32_e32 v25, 64, v12
	v_cmp_lt_i32_e32 vcc, v13, v25
	s_waitcnt lgkmcnt(0)
	v_pk_mul_f32 v[14:15], v[6:7], v[6:7]
	v_xor_b32_e32 v23, 2, v223
	v_cndmask_b32_e32 v12, v223, v13, vcc
	v_lshlrev_b32_e32 v21, 2, v12
	v_pk_mul_f32 v[12:13], v[8:9], v[8:9]
	v_cmp_lt_i32_e32 vcc, v23, v25
	v_pk_mov_b32 v[16:17], v[14:15], v[12:13] op_sel:[1,0]
	v_mov_b32_e32 v15, v13
	v_pk_add_f32 v[12:13], v[16:17], v[14:15]
	v_cndmask_b32_e32 v15, v223, v23, vcc
	v_add_f32_e32 v12, v12, v13
	ds_bpermute_b32 v13, v21, v12
	v_lshlrev_b32_e32 v23, 2, v15
	v_xor_b32_e32 v24, 4, v223
	v_cmp_lt_i32_e32 vcc, v24, v25
	v_xor_b32_e32 v14, 8, v223
	s_waitcnt lgkmcnt(0)
	v_add_f32_e32 v12, v12, v13
	ds_bpermute_b32 v13, v23, v12
	v_cndmask_b32_e32 v16, v223, v24, vcc
	v_lshlrev_b32_e32 v24, 2, v16
	v_cmp_lt_i32_e64 s[40:41], v14, v25
	v_xor_b32_e32 v15, 16, v223
	s_waitcnt lgkmcnt(0)
	v_add_f32_e32 v12, v12, v13
	s_nop 1
	v_cndmask_b32_e64 v14, v223, v14, s[40:41]
	v_cmp_lt_i32_e32 vcc, v15, v25
	v_lshlrev_b32_e32 v25, 2, v14
	v_add_f32_dpp v14, v12, v12 row_half_mirror row_mask:0xf bank_mask:0xf
	ds_bpermute_b32 v16, v25, v14
	v_cndmask_b32_e32 v15, v223, v15, vcc
	v_lshlrev_b32_e32 v26, 2, v15
	v_or_b32_e32 v12, 1, v18
	v_ashrrev_i32_e32 v13, 31, v12
	s_waitcnt lgkmcnt(0)
; #define LAS __attribute__((address_space(3)))
; __device__ __forceinline__ float bflo(unsigned w) { return __uint_as_float(w << 16); }
; __device__ __forceinline__ float bfhi(unsigned w) { return __uint_as_float(w & 0xffff0000u); }
; __device__ __forceinline__ unsigned cvt_pk_bf16(float lo, float hi) { unsigned r; asm volatile("v_cvt_pk_bf16_f32 %0, %1, %2" : "=v"(r) : "v"(lo), "v"(hi)); return r; }
; __device__ __forceinline__ float silu_f(float g) { return g * __builtin_amdgcn_rcpf(1.f + __expf(-g)); }
; __device__ __forceinline__ void gla_p3(CArgs& a, int l, int cc, int h, LAS float* L) {
;     ...
;     for (int r = 0; r < 4; ++r) { const f32x4 o = *(const LAS f32x4*)(L + (i0 + r) * 128 + e4);
;         float ss = (o.x * o.x + o.y * o.y) + (o.z * o.z + o.w * o.w);
; #pragma unroll
;         for (int m = 1; m < 32; m <<= 1) ss += __shfl_xor(ss, m);
;         const float rs = rsqrtf(ss * (1.f / 128.f) + EPS);
;         const size_t row = (size_t)cc * 64 + i0 + r;
;         const u32x2 gw = *(const u32x2*)(P + (size_t)(i0 + r) * INP + C_CG + h * 128 + e4);
;         const f32x4 y = o * rs * gn;
;         u32x2 w; w.x = cvt_pk_bf16(y.x * silu_f(bflo(gw.x)), y.y * silu_f(bfhi(gw.x))); w.y = cvt_pk_bf16(y.z * silu_f(bflo(gw.y)), y.w * silu_f(bfhi(gw.y)));
;         *(u32x2*)(Z + row * DM + 1536 + h * 128 + e4) = w; }
	v_add_f32_e32 v16, v14, v16
	ds_bpermute_b32 v17, v26, v16
	v_lshlrev_b64 v[14:15], 13, v[12:13]
	v_lshl_add_u64 v[14:15], s[20:21], 0, v[14:15]
	v_lshl_add_u64 v[14:15], v[14:15], 0, s[18:19]
	v_lshl_add_u64 v[14:15], v[14:15], 0, v[0:1]
	s_waitcnt lgkmcnt(0)
	v_add_f32_e32 v13, v16, v17
	v_fmamk_f32 v13, v13, 0x3c000000, v216
	v_cmp_gt_f32_e32 vcc, s26, v13
	v_mul_f32_e32 v16, 0x4b800000, v13
	s_nop 0
	v_cndmask_b32_e32 v13, v13, v16, vcc
	v_rsq_f32_e32 v13, v13
	v_add_co_u32_e64 v16, s[40:41], s10, v14
	v_mul_f32_e32 v14, 0x45800000, v13
	v_cndmask_b32_e32 v14, v13, v14, vcc
	v_pk_mul_f32 v[6:7], v[6:7], v[14:15] op_sel_hi:[1,0]
	v_pk_mul_f32 v[8:9], v[8:9], v[14:15] op_sel_hi:[1,0]
	v_addc_co_u32_e64 v17, s[40:41], 0, v15, s[40:41]
	s_waitcnt vmcnt(1)
	v_lshlrev_b32_e32 v13, 16, v10
	v_and_b32_e32 v10, 0xffff0000, v10
	v_lshlrev_b32_e32 v14, 16, v11
	v_and_b32_e32 v11, 0xffff0000, v11
	v_mul_f32_e32 v15, 0xbfb8aa3b, v13
	v_mul_f32_e32 v27, 0xbfb8aa3b, v10
	v_mul_f32_e32 v28, 0xbfb8aa3b, v14
	v_mul_f32_e32 v29, 0xbfb8aa3b, v11
	v_exp_f32_e32 v15, v15
	v_exp_f32_e32 v27, v27
	v_exp_f32_e32 v28, v28
	v_exp_f32_e32 v29, v29
	v_add_f32_e32 v15, 1.0, v15
	v_add_f32_e32 v27, 1.0, v27
	v_add_f32_e32 v28, 1.0, v28
	v_add_f32_e32 v29, 1.0, v29
	v_rcp_f32_e32 v15, v15
	v_rcp_f32_e32 v27, v27
	v_rcp_f32_e32 v28, v28
	v_rcp_f32_e32 v29, v29
	s_waitcnt vmcnt(0)
	v_pk_mul_f32 v[8:9], v[4:5], v[8:9]
	v_pk_mul_f32 v[6:7], v[2:3], v[6:7]
	v_mul_f32_e32 v13, v15, v13
	v_mul_f32_e32 v10, v27, v10
	v_mul_f32_e32 v14, v28, v14
	v_mul_f32_e32 v11, v29, v11
	v_mul_f32_e32 v6, v13, v6
	v_mul_f32_e32 v7, v10, v7
	v_mul_f32_e32 v8, v14, v8
	v_mul_f32_e32 v9, v11, v9
	v_cvt_pk_bf16_f32 v14, v6, v7
	v_cvt_pk_bf16_f32 v15, v8, v9
	v_mov_b64_e32 v[16:17], v[80:81]
	v_lshl_add_u32 v6, v12, 9, v22
	ds_read_b128 v[6:9], v6
	s_waitcnt lgkmcnt(0)
	v_pk_mul_f32 v[10:11], v[8:9], v[8:9]
	v_pk_mul_f32 v[12:13], v[6:7], v[6:7]
	s_nop 0
	v_pk_mov_b32 v[28:29], v[12:13], v[10:11] op_sel:[1,0]
	v_mov_b32_e32 v13, v11
	v_pk_add_f32 v[10:11], v[28:29], v[12:13]
	v_or_b32_e32 v12, 2, v18
	v_add_f32_e32 v10, v10, v11
	s_nop 1
	v_ashrrev_i32_e32 v13, 31, v12
	v_add_f32_dpp v27, v10, v10 quad_perm:[1,0,3,2] row_mask:0xf bank_mask:0xf
	ds_bpermute_b32 v28, v23, v27
	v_lshlrev_b64 v[10:11], 12, v[18:19]
	v_lshlrev_b64 v[18:19], 13, v[12:13]
	v_lshl_add_u64 v[10:11], s[4:5], 0, v[10:11]
	v_lshl_add_u64 v[10:11], v[10:11], 0, s[18:19]
	s_waitcnt lgkmcnt(0)
	v_add_f32_e32 v27, v27, v28
	ds_bpermute_b32 v28, v24, v27
	v_lshl_add_u64 v[10:11], v[10:11], 0, v[0:1]
	s_mov_b32 s4, 0xb900000
	v_lshl_add_u64 v[18:19], s[20:21], 0, v[18:19]
	v_lshl_add_u64 v[18:19], v[18:19], 0, s[18:19]
	s_waitcnt lgkmcnt(0)
	v_add_f32_e32 v13, v27, v28
	ds_bpermute_b32 v27, v25, v13
	v_add_co_u32_e32 v28, vcc, s4, v10
	v_lshl_add_u64 v[18:19], v[18:19], 0, v[0:1]
	s_nop 0
	v_addc_co_u32_e32 v29, vcc, 0, v11, vcc
	s_waitcnt lgkmcnt(0)
	v_add_f32_e32 v13, v13, v27
	ds_bpermute_b32 v27, v26, v13
	global_store_dwordx2 v[28:29], v[14:15], off offset:3072
	v_add_co_u32_e32 v18, vcc, s10, v18
	s_mov_b32 s4, 0xb901000
	s_waitcnt lgkmcnt(0)
	v_add_f32_e32 v13, v13, v27
	v_fmamk_f32 v13, v13, 0x3c000000, v216
	v_cmp_gt_f32_e64 s[40:41], s26, v13
	v_mul_f32_e32 v27, 0x4b800000, v13
	v_addc_co_u32_e32 v19, vcc, 0, v19, vcc
	v_cndmask_b32_e64 v13, v13, v27, s[40:41]
	v_rsq_f32_e32 v13, v13
	s_nop 0
	v_mul_f32_e32 v14, 0x45800000, v13
	v_cndmask_b32_e64 v14, v13, v14, s[40:41]
	v_pk_mul_f32 v[6:7], v[6:7], v[14:15] op_sel_hi:[1,0]
	v_pk_mul_f32 v[8:9], v[8:9], v[14:15] op_sel_hi:[1,0]
	v_pk_mul_f32 v[6:7], v[2:3], v[6:7]
	v_pk_mul_f32 v[8:9], v[4:5], v[8:9]
	s_waitcnt vmcnt(1)
	v_lshlrev_b32_e32 v13, 16, v16
	v_and_b32_e32 v14, 0xffff0000, v16
	v_and_b32_e32 v16, 0xffff0000, v17
	v_lshlrev_b32_e32 v15, 16, v17
	v_mul_f32_e32 v29, 0xbfb8aa3b, v16
	v_mul_f32_e32 v17, 0xbfb8aa3b, v13
	v_mul_f32_e32 v27, 0xbfb8aa3b, v14
	v_mul_f32_e32 v28, 0xbfb8aa3b, v15
	v_exp_f32_e32 v29, v29
	v_exp_f32_e32 v17, v17
	v_exp_f32_e32 v27, v27
	v_exp_f32_e32 v28, v28
	v_add_f32_e32 v29, 1.0, v29
	v_add_f32_e32 v17, 1.0, v17
	v_add_f32_e32 v27, 1.0, v27
	v_add_f32_e32 v28, 1.0, v28
	v_rcp_f32_e32 v29, v29
	v_rcp_f32_e32 v17, v17
	v_rcp_f32_e32 v27, v27
	v_rcp_f32_e32 v28, v28
	v_mul_f32_e32 v16, v29, v16
	v_mul_f32_e32 v13, v17, v13
	v_mul_f32_e32 v14, v27, v14
	v_mul_f32_e32 v15, v28, v15
	v_mul_f32_e32 v9, v16, v9
	v_mul_f32_e32 v6, v13, v6
	v_mul_f32_e32 v7, v14, v7
	v_mul_f32_e32 v13, v15, v8
	v_cvt_pk_bf16_f32 v8, v6, v7
	v_cvt_pk_bf16_f32 v9, v13, v9
	v_mov_b64_e32 v[16:17], v[82:83]
	v_lshl_add_u32 v6, v12, 9, v22
	ds_read_b128 v[12:15], v6
	s_waitcnt lgkmcnt(0)
; #define LAS __attribute__((address_space(3)))
; __device__ __forceinline__ float bflo(unsigned w) { return __uint_as_float(w << 16); }
; __device__ __forceinline__ float bfhi(unsigned w) { return __uint_as_float(w & 0xffff0000u); }
; __device__ __forceinline__ unsigned cvt_pk_bf16(float lo, float hi) { unsigned r; asm volatile("v_cvt_pk_bf16_f32 %0, %1, %2" : "=v"(r) : "v"(lo), "v"(hi)); return r; }
; __device__ __forceinline__ float silu_f(float g) { return g * __builtin_amdgcn_rcpf(1.f + __expf(-g)); }
; __device__ __forceinline__ void gla_p3(CArgs& a, int l, int cc, int h, LAS float* L) {
;     ...
;     for (int r = 0; r < 4; ++r) { const f32x4 o = *(const LAS f32x4*)(L + (i0 + r) * 128 + e4);
;         float ss = (o.x * o.x + o.y * o.y) + (o.z * o.z + o.w * o.w);
; #pragma unroll
;         for (int m = 1; m < 32; m <<= 1) ss += __shfl_xor(ss, m);
;         const float rs = rsqrtf(ss * (1.f / 128.f) + EPS);
;         const size_t row = (size_t)cc * 64 + i0 + r;
;         const u32x2 gw = *(const u32x2*)(P + (size_t)(i0 + r) * INP + C_CG + h * 128 + e4);
;         const f32x4 y = o * rs * gn;
;         u32x2 w; w.x = cvt_pk_bf16(y.x * silu_f(bflo(gw.x)), y.y * silu_f(bfhi(gw.x))); w.y = cvt_pk_bf16(y.z * silu_f(bflo(gw.y)), y.w * silu_f(bfhi(gw.y)));
;         *(u32x2*)(Z + row * DM + 1536 + h * 128 + e4) = w; }
	v_pk_mul_f32 v[6:7], v[14:15], v[14:15]
	v_pk_mul_f32 v[18:19], v[12:13], v[12:13]
	s_nop 0
	v_pk_mov_b32 v[28:29], v[18:19], v[6:7] op_sel:[1,0]
	v_mov_b32_e32 v19, v7
	v_pk_add_f32 v[6:7], v[28:29], v[18:19]
	s_nop 0
	v_add_f32_e32 v6, v6, v7
	s_nop 1
	v_add_f32_dpp v6, v6, v6 quad_perm:[1,0,3,2] row_mask:0xf bank_mask:0xf
	s_nop 1
	v_add_f32_dpp v27, v6, v6 quad_perm:[2,3,0,1] row_mask:0xf bank_mask:0xf
	ds_bpermute_b32 v28, v24, v27
	v_or_b32_e32 v6, 3, v20
	v_ashrrev_i32_e32 v7, 31, v6
	v_lshlrev_b64 v[18:19], 13, v[6:7]
	v_lshl_add_u64 v[18:19], s[20:21], 0, v[18:19]
	s_waitcnt lgkmcnt(0)
	v_add_f32_e32 v7, v27, v28
	s_nop 1
	v_lshl_add_u64 v[18:19], v[18:19], 0, s[18:19]
	v_lshl_add_u64 v[18:19], v[18:19], 0, v[0:1]
	v_add_co_u32_e32 v28, vcc, s4, v10
	v_add_f32_dpp v0, v7, v7 row_mirror row_mask:0xf bank_mask:0xf
	ds_bpermute_b32 v7, v26, v0
	v_addc_co_u32_e32 v29, vcc, 0, v11, vcc
	global_store_dwordx2 v[28:29], v[8:9], off offset:3072
	v_add_co_u32_e64 v18, s[40:41], s10, v18
	s_waitcnt lgkmcnt(0)
	v_add_f32_e32 v0, v0, v7
	v_fmamk_f32 v0, v0, 0x3c000000, v216
	v_cmp_gt_f32_e32 vcc, s26, v0
	v_mul_f32_e32 v7, 0x4b800000, v0
	v_addc_co_u32_e64 v19, s[40:41], 0, v19, s[40:41]
	v_cndmask_b32_e32 v0, v0, v7, vcc
	v_rsq_f32_e32 v0, v0
	s_mov_b32 s4, 0xb902000
	v_mul_f32_e32 v7, 0x45800000, v0
	v_cndmask_b32_e32 v0, v0, v7, vcc
	v_pk_mul_f32 v[8:9], v[12:13], v[0:1] op_sel_hi:[1,0]
	v_pk_mul_f32 v[12:13], v[14:15], v[0:1] op_sel_hi:[1,0]
	v_pk_mul_f32 v[8:9], v[2:3], v[8:9]
	v_pk_mul_f32 v[12:13], v[4:5], v[12:13]
	s_waitcnt vmcnt(1)
	v_lshlrev_b32_e32 v0, 16, v16
	v_and_b32_e32 v7, 0xffff0000, v16
	v_lshlrev_b32_e32 v14, 16, v17
	v_and_b32_e32 v15, 0xffff0000, v17
	v_mul_f32_e32 v16, 0xbfb8aa3b, v0
	v_mul_f32_e32 v17, 0xbfb8aa3b, v7
	v_mul_f32_e32 v20, 0xbfb8aa3b, v14
	v_mul_f32_e32 v27, 0xbfb8aa3b, v15
	v_exp_f32_e32 v16, v16
	v_exp_f32_e32 v17, v17
	v_exp_f32_e32 v20, v20
	v_exp_f32_e32 v27, v27
	v_add_f32_e32 v16, 1.0, v16
	v_add_f32_e32 v17, 1.0, v17
	v_add_f32_e32 v20, 1.0, v20
	v_add_f32_e32 v27, 1.0, v27
	v_rcp_f32_e32 v16, v16
	v_rcp_f32_e32 v17, v17
	v_rcp_f32_e32 v20, v20
	v_rcp_f32_e32 v27, v27
	v_mul_f32_e32 v0, v16, v0
	v_mul_f32_e32 v7, v17, v7
	v_mul_f32_e32 v14, v20, v14
	v_mul_f32_e32 v15, v27, v15
	v_mul_f32_e32 v0, v0, v8
	v_mul_f32_e32 v7, v7, v9
	v_mul_f32_e32 v8, v14, v12
	v_mul_f32_e32 v9, v15, v13
	v_cvt_pk_bf16_f32 v12, v0, v7
	v_cvt_pk_bf16_f32 v13, v8, v9
	v_mov_b64_e32 v[14:15], v[84:85]
	v_lshl_add_u32 v0, v6, 9, v22
	ds_read_b128 v[6:9], v0
	s_waitcnt lgkmcnt(0)
	v_pk_mul_f32 v[16:17], v[8:9], v[8:9]
	v_pk_mul_f32 v[18:19], v[6:7], v[6:7]
	s_nop 0
	v_pk_mov_b32 v[28:29], v[18:19], v[16:17] op_sel:[1,0]
	v_mov_b32_e32 v19, v17
	v_pk_add_f32 v[16:17], v[28:29], v[18:19]
	s_nop 0
	v_add_f32_e32 v0, v16, v17
	s_nop 1
	v_add_f32_dpp v0, v0, v0 quad_perm:[1,0,3,2] row_mask:0xf bank_mask:0xf
	s_nop 1
	v_add_f32_dpp v0, v0, v0 quad_perm:[2,3,0,1] row_mask:0xf bank_mask:0xf
	s_nop 1
	v_add_f32_dpp v0, v0, v0 row_half_mirror row_mask:0xf bank_mask:0xf
	s_nop 1
	v_add_co_u32_e64 v16, s[40:41], s4, v10
	v_add_co_u32_e32 v10, vcc, 0xb903000, v10
	v_add_f32_dpp v0, v0, v0 row_mirror row_mask:0xf bank_mask:0xf
	ds_bpermute_b32 v18, v26, v0
	v_addc_co_u32_e64 v17, s[40:41], 0, v11, s[40:41]
	global_store_dwordx2 v[16:17], v[12:13], off offset:3072
	v_addc_co_u32_e32 v11, vcc, 0, v11, vcc
	s_waitcnt lgkmcnt(0)
	v_add_f32_e32 v0, v0, v18
	v_fmamk_f32 v0, v0, 0x3c000000, v216
	v_cmp_gt_f32_e64 s[40:41], s26, v0
	v_mul_f32_e32 v18, 0x4b800000, v0
	s_nop 0
	v_cndmask_b32_e64 v0, v0, v18, s[40:41]
	v_rsq_f32_e32 v0, v0
	s_nop 0
	v_mul_f32_e32 v12, 0x45800000, v0
	v_cndmask_b32_e64 v0, v0, v12, s[40:41]
	v_pk_mul_f32 v[6:7], v[6:7], v[0:1] op_sel_hi:[1,0]
	v_pk_mul_f32 v[8:9], v[8:9], v[0:1] op_sel_hi:[1,0]
	v_pk_mul_f32 v[2:3], v[2:3], v[6:7]
	v_pk_mul_f32 v[4:5], v[4:5], v[8:9]
	s_waitcnt vmcnt(1)
	v_lshlrev_b32_e32 v0, 16, v14
	v_and_b32_e32 v6, 0xffff0000, v14
	v_lshlrev_b32_e32 v7, 16, v15
	v_and_b32_e32 v8, 0xffff0000, v15
	v_mul_f32_e32 v9, 0xbfb8aa3b, v0
	v_mul_f32_e32 v12, 0xbfb8aa3b, v6
	v_mul_f32_e32 v13, 0xbfb8aa3b, v7
	v_mul_f32_e32 v14, 0xbfb8aa3b, v8
	v_exp_f32_e32 v9, v9
	v_exp_f32_e32 v12, v12
	v_exp_f32_e32 v13, v13
	v_exp_f32_e32 v14, v14
	v_add_f32_e32 v9, 1.0, v9
	v_add_f32_e32 v12, 1.0, v12
	v_add_f32_e32 v13, 1.0, v13
	v_add_f32_e32 v14, 1.0, v14
	v_rcp_f32_e32 v9, v9
	v_rcp_f32_e32 v12, v12
	v_rcp_f32_e32 v13, v13
	v_rcp_f32_e32 v14, v14
	v_mul_f32_e32 v0, v9, v0
	v_mul_f32_e32 v6, v12, v6
	v_mul_f32_e32 v7, v13, v7
	v_mul_f32_e32 v8, v14, v8
	v_mul_f32_e32 v0, v0, v2
	v_mul_f32_e32 v2, v6, v3
	v_mul_f32_e32 v3, v7, v4
	v_mul_f32_e32 v4, v8, v5
	v_cvt_pk_bf16_f32 v2, v0, v2
	v_cvt_pk_bf16_f32 v3, v3, v4
	global_store_dwordx2 v[10:11], v[2:3], off offset:3072
	s_branch .LBB0_70
